# retention output: gate rows loaded early without SGPR temps, group-norm weights loaded before the barrier
# speedup vs baseline: 1.0068x; 1.0059x over previous
.LBB0_802:
	s_and_b32 s12, s11, 3
	v_cvt_f32_ubyte0_e32 v0, s12
	v_sub_f32_e32 v0, 0xc0a00000, v0
	v_cmp_gt_f32_e32 vcc, s20, v0
	s_ashr_i32 s8, s11, 6
	s_ashr_i32 s9, s8, 31
	v_cndmask_b32_e32 v1, 0, v228, vcc
	v_add_f32_e32 v0, v0, v1
	s_lshl_b64 s[0:1], s[8:9], 11
	s_and_b32 s13, s10, 0x780
	v_exp_f32_e32 v0, v0
	s_or_b32 s0, s0, s13
	s_and_b64 s[14:15], vcc, exec
	s_cselect_b32 s9, 0xffffffc0, 0
	v_ldexp_f32 v16, v0, s9
	v_sub_f32_e32 v2, 1.0, v16
	v_add_f32_e32 v0, -1.0, v2
	v_sub_f32_e32 v1, v0, v2
	v_add_f32_e32 v1, 1.0, v1
	v_sub_f32_e64 v0, -v16, v0
	v_add_f32_e32 v3, v0, v1
	v_frexp_mant_f32_e32 v0, v2
	v_cmp_gt_f32_e32 vcc, s17, v0
	v_cvt_f64_f32_e32 v[0:1], v2
	v_frexp_exp_i32_f64_e32 v0, v[0:1]
	v_subbrev_co_u32_e32 v8, vcc, 0, v0, vcc
	v_sub_u32_e32 v0, 0, v8
	v_ldexp_f32 v1, v2, v0
	v_add_f32_e32 v2, -1.0, v1
	v_add_f32_e32 v4, 1.0, v1
	v_ldexp_f32 v0, v3, v0
	v_add_f32_e32 v3, 1.0, v2
	v_add_f32_e32 v5, -1.0, v4
	v_sub_f32_e32 v3, v1, v3
	v_sub_f32_e32 v1, v1, v5
	v_add_f32_e32 v3, v0, v3
	v_add_f32_e32 v0, v0, v1
	v_add_f32_e32 v9, v4, v0
	v_rcp_f32_e32 v11, v9
	v_sub_f32_e32 v1, v9, v4
	v_sub_f32_e32 v10, v0, v1
	v_add_f32_e32 v1, v2, v3
	v_mul_f32_e32 v13, v1, v11
	v_sub_f32_e32 v0, v1, v2
	v_mul_f32_e32 v2, v9, v13
	v_fma_f32 v4, v13, v9, -v2
	v_fmac_f32_e32 v4, v13, v10
	v_sub_f32_e32 v12, v3, v0
	v_add_f32_e32 v0, v2, v4
	v_sub_f32_e32 v3, v1, v0
	v_pk_add_f32 v[6:7], v[0:1], v[2:3] neg_lo:[0,1] neg_hi:[0,1]
	v_mov_b32_e32 v5, v0
	v_pk_add_f32 v[0:1], v[6:7], v[4:5] neg_lo:[0,1] neg_hi:[0,1]
	v_cmp_nlt_f32_e32 vcc, 1.0, v16
	v_add_f32_e32 v1, v12, v1
	v_add_f32_e32 v0, v0, v1
	v_add_f32_e32 v1, v3, v0
	v_mul_f32_e32 v12, v11, v1
	v_mul_f32_e32 v2, v9, v12
	v_fma_f32 v4, v12, v9, -v2
	v_fmac_f32_e32 v4, v12, v10
	v_sub_f32_e32 v3, v3, v1
	v_add_f32_e32 v9, v0, v3
	v_add_f32_e32 v0, v2, v4
	v_sub_f32_e32 v3, v1, v0
	v_pk_add_f32 v[6:7], v[0:1], v[2:3] neg_lo:[0,1] neg_hi:[0,1]
	v_mov_b32_e32 v5, v0
	v_pk_add_f32 v[0:1], v[6:7], v[4:5] neg_lo:[0,1] neg_hi:[0,1]
	v_mov_b64_e32 v[98:99], s[6:7]
	v_add_f32_e32 v1, v9, v1
	v_add_f32_e32 v0, v0, v1
	v_add_f32_e32 v1, v13, v12
	v_add_f32_e32 v0, v3, v0
	v_sub_f32_e32 v2, v1, v13
	v_mul_f32_e32 v0, v11, v0
	v_sub_f32_e32 v2, v12, v2
	v_add_f32_e32 v2, v2, v0
	v_add_f32_e32 v4, v1, v2
	v_mul_f32_e32 v5, v4, v4
	v_fmamk_f32 v0, v5, 0x3e9b6dac, v222
	v_fmaak_f32 v185, v5, v0, 0x3f2aaada
	v_cvt_f32_i32_e32 v0, v8
	v_sub_f32_e32 v1, v4, v1
	v_sub_f32_e32 v1, v2, v1
	v_ldexp_f32 v6, v1, 1
	v_mul_f32_e32 v1, v4, v5
	v_ldexp_f32 v3, v4, 1
	v_pk_mul_f32 v[4:5], v[0:1], v[184:185]
	s_lshl_b32 s88, s12, 8
	v_fma_f32 v2, v0, s23, -v4
	v_fmac_f32_e32 v2, 0xb102e308, v0
	v_pk_add_f32 v[0:1], v[4:5], v[2:3]
	v_add_u32_e32 v185, 0, v100
	v_sub_f32_e32 v3, v1, v3
	v_sub_f32_e32 v3, v5, v3
	v_add_f32_e32 v7, v6, v3
	v_mov_b32_e32 v6, v4
	v_pk_add_f32 v[4:5], v[0:1], v[4:5] neg_lo:[0,1] neg_hi:[0,1]
	v_pk_add_f32 v[8:9], v[0:1], v[6:7]
	v_mov_b32_e32 v3, v0
	v_mov_b32_e32 v5, v9
	v_pk_add_f32 v[10:11], v[2:3], v[4:5] neg_lo:[0,1] neg_hi:[0,1]
	v_pk_add_f32 v[2:3], v[2:3], v[4:5]
	v_mov_b32_e32 v14, v1
	v_pk_add_f32 v[4:5], v[2:3], v[0:1] op_sel:[1,0] op_sel_hi:[0,1] neg_lo:[0,1] neg_hi:[0,1]
	v_pk_add_f32 v[12:13], v[8:9], v[4:5] op_sel_hi:[1,0] neg_lo:[0,1] neg_hi:[0,1]
	v_mov_b32_e32 v8, v9
	v_mov_b32_e32 v9, v3
	v_mov_b32_e32 v15, v4
	v_pk_add_f32 v[4:5], v[8:9], v[14:15] neg_lo:[0,1] neg_hi:[0,1]
	v_mov_b32_e32 v6, v7
	v_mov_b32_e32 v7, v0
	v_pk_add_f32 v[0:1], v[6:7], v[4:5] neg_lo:[0,1] neg_hi:[0,1]
	v_mov_b32_e32 v12, v10
	v_pk_add_f32 v[4:5], v[12:13], v[0:1]
	v_mov_b32_e32 v11, v3
	v_pk_add_f32 v[6:7], v[4:5], v[4:5] op_sel:[0,1] op_sel_hi:[1,0]
	s_lshl_b32 s8, s8, 2
	v_pk_add_f32 v[2:3], v[2:3], v[6:7] op_sel:[1,0] op_sel_hi:[0,1]
	v_mov_b32_e32 v5, v2
	v_pk_add_f32 v[8:9], v[4:5], v[10:11] neg_lo:[0,1] neg_hi:[0,1]
	v_mov_b32_e32 v1, v6
	v_sub_f32_e32 v3, v4, v8
	v_pk_add_f32 v[0:1], v[0:1], v[8:9] neg_lo:[0,1] neg_hi:[0,1]
	v_sub_f32_e32 v3, v10, v3
	v_add_f32_e32 v0, v0, v3
	v_add_f32_e32 v0, v0, v1
	v_add_f32_e32 v0, v2, v0
	v_cndmask_b32_e32 v0, v225, v0, vcc
	v_cmp_neq_f32_e32 vcc, 1.0, v16
	s_or_b32 s8, s8, s12
	v_add_u32_e32 v197, 0, v101
	v_cndmask_b32_e32 v0, v229, v0, vcc
	v_cmp_gt_f32_e32 vcc, s25, v16
	s_ashr_i32 s9, s8, 31
	v_add_u32_e32 v198, 0, v102
	v_cndmask_b32_e64 v200, v0, -v16, vcc
	v_lshl_add_u64 v[0:1], s[0:1], 0, v[82:83]
	v_mad_u64_u32 v[2:3], s[14:15], v0, s97, v[98:99]
	v_mad_i32_i24 v3, v1, s97, v3
	v_lshl_add_u64 v[0:1], v[2:3], 0, s[88:89]
	v_lshl_add_u64 v[0:1], v[0:1], 0, v[32:33]
	v_add_co_u32_e32 v2, vcc, s93, v0
	s_lshl_b64 s[8:9], s[8:9], 11
	s_nop 0
	v_addc_co_u32_e32 v3, vcc, 0, v1, vcc
	v_add_co_u32_e32 v0, vcc, s96, v0
	global_load_dwordx4 v[42:45], v[2:3], off offset:3072
	s_nop 0
	v_addc_co_u32_e32 v1, vcc, 0, v1, vcc
	global_load_dwordx4 v[46:49], v[0:1], off
	global_load_dwordx4 v[28:31], v[0:1], off offset:1024
	v_lshl_add_u64 v[0:1], s[0:1], 0, v[92:93]
	v_mad_u64_u32 v[2:3], s[14:15], v0, s97, v[98:99]
	v_mad_i32_i24 v3, v1, s97, v3
	v_lshl_add_u64 v[0:1], v[2:3], 0, s[88:89]
	v_lshl_add_u64 v[0:1], v[0:1], 0, v[32:33]
	v_add_co_u32_e32 v2, vcc, s93, v0
	v_add_u32_e32 v199, 0, v103
	s_nop 0
	v_addc_co_u32_e32 v3, vcc, 0, v1, vcc
	v_add_co_u32_e32 v0, vcc, s96, v0
	global_load_dwordx4 v[34:37], v[2:3], off offset:3072
	s_nop 0
	v_addc_co_u32_e32 v1, vcc, 0, v1, vcc
	global_load_dwordx4 v[38:41], v[0:1], off
	global_load_dwordx4 v[16:19], v[0:1], off offset:1024
	v_lshl_add_u64 v[0:1], s[0:1], 0, v[94:95]
	v_mad_u64_u32 v[2:3], s[14:15], v0, s97, v[98:99]
	v_mad_i32_i24 v3, v1, s97, v3
	v_lshl_add_u64 v[0:1], v[2:3], 0, s[88:89]
	v_lshl_add_u64 v[0:1], v[0:1], 0, v[32:33]
	v_add_co_u32_e32 v2, vcc, s93, v0
	s_or_b32 s8, s8, s13
	s_nop 0
	v_addc_co_u32_e32 v3, vcc, 0, v1, vcc
	v_add_co_u32_e32 v0, vcc, s96, v0
	global_load_dwordx4 v[20:23], v[2:3], off offset:3072
	s_nop 0
	v_addc_co_u32_e32 v1, vcc, 0, v1, vcc
	global_load_dwordx4 v[24:27], v[0:1], off
	global_load_dwordx4 v[4:7], v[0:1], off offset:1024
	v_lshl_add_u64 v[0:1], s[0:1], 0, v[96:97]
	v_mad_u64_u32 v[2:3], s[14:15], v0, s97, v[98:99]
	v_mad_i32_i24 v3, v1, s97, v3
	v_lshl_add_u64 v[0:1], v[2:3], 0, s[88:89]
	v_lshl_add_u64 v[0:1], v[0:1], 0, v[32:33]
	v_add_co_u32_e32 v2, vcc, s93, v0
	v_mul_f32_e32 v200, 0x3fb8aa3b, v200
	s_nop 0
	v_addc_co_u32_e32 v3, vcc, 0, v1, vcc
	v_add_co_u32_e32 v0, vcc, s96, v0
	global_load_dwordx4 v[8:11], v[2:3], off offset:3072
	s_nop 0
	v_addc_co_u32_e32 v1, vcc, 0, v1, vcc
	global_load_dwordx4 v[12:15], v[0:1], off
	s_nop 0
	global_load_dwordx4 v[0:3], v[0:1], off offset:1024
	s_barrier
	s_waitcnt vmcnt(11)
	ds_write_b128 v185, v[42:45]
	s_waitcnt vmcnt(10)
	ds_write_b128 v185, v[46:49] offset:34816
	v_add_u32_e32 v42, s22, v100
	s_waitcnt vmcnt(9)
	ds_write_b128 v42, v[28:31]
	v_add_u32_e32 v28, s22, v101
	s_waitcnt vmcnt(8)
	ds_write_b128 v197, v[34:37]
	s_waitcnt vmcnt(7)
	ds_write_b128 v197, v[38:41] offset:34816
	s_waitcnt vmcnt(6)
	ds_write_b128 v28, v[16:19]
	v_add_u32_e32 v16, s22, v102
	s_waitcnt vmcnt(5)
	ds_write_b128 v198, v[20:23]
	s_waitcnt vmcnt(4)
	ds_write_b128 v198, v[24:27] offset:34816
	s_waitcnt vmcnt(3)
	ds_write_b128 v16, v[4:7]
	v_add_u32_e32 v4, s22, v103
	s_waitcnt vmcnt(2)
	ds_write_b128 v199, v[8:11]
	s_waitcnt vmcnt(1)
	ds_write_b128 v199, v[12:15] offset:34816
	s_waitcnt vmcnt(0)
	ds_write_b128 v4, v[0:3]
	v_lshl_add_u64 v[0:1], s[8:9], 0, v[82:83]
	v_lshlrev_b64 v[0:1], 8, v[0:1]
	v_lshl_add_u64 v[2:3], v[84:85], 0, v[0:1]
	v_lshl_add_u64 v[0:1], v[86:87], 0, v[0:1]
	global_load_dwordx4 v[16:19], v[2:3], off
	global_load_dwordx4 v[34:37], v[0:1], off
	v_lshl_add_u64 v[0:1], s[8:9], 0, v[92:93]
	v_lshlrev_b64 v[0:1], 8, v[0:1]
	v_lshl_add_u64 v[2:3], v[84:85], 0, v[0:1]
	v_lshl_add_u64 v[0:1], v[86:87], 0, v[0:1]
	global_load_dwordx4 v[20:23], v[2:3], off
	global_load_dwordx4 v[38:41], v[0:1], off
	v_lshl_add_u64 v[0:1], s[8:9], 0, v[94:95]
	v_lshlrev_b64 v[0:1], 8, v[0:1]
	v_lshl_add_u64 v[2:3], v[84:85], 0, v[0:1]
	v_lshl_add_u64 v[0:1], v[86:87], 0, v[0:1]
	global_load_dwordx4 v[24:27], v[2:3], off
	global_load_dwordx4 v[42:45], v[0:1], off
	v_lshl_add_u64 v[0:1], s[8:9], 0, v[96:97]
	v_lshlrev_b64 v[0:1], 8, v[0:1]
	v_lshl_add_u64 v[2:3], v[84:85], 0, v[0:1]
	v_lshl_add_u64 v[0:1], v[86:87], 0, v[0:1]
	global_load_dwordx4 v[28:31], v[2:3], off
	global_load_dwordx4 v[78:81], v[0:1], off
	s_waitcnt lgkmcnt(0)
	s_barrier
	ds_read_b128 v[74:77], v173
	ds_read_b128 v[70:73], v173 offset:32
	ds_read_b128 v[66:69], v173 offset:64
	ds_read_b128 v[62:65], v173 offset:96
	ds_read_b128 v[58:61], v173 offset:128
	ds_read_b128 v[54:57], v173 offset:160
	ds_read_b128 v[50:53], v173 offset:192
	ds_read_b128 v[46:49], v173 offset:224
	ds_read_b128 v[0:3], v174 offset:34816
	ds_read_b128 v[202:205], v174 offset:34848
	s_waitcnt lgkmcnt(1)
	v_mfma_f32_32x32x16_bf16 v[0:15], v[0:3], v[74:77], 0
	v_mul_f32_e32 v201, v200, v104
	v_exp_f32_e32 v201, v201
	s_lshl_b32 s8, s12, 9
	s_mov_b32 s9, s89
	s_add_i32 s11, s11, s28
	s_add_i32 s10, s10, s16
	s_cmpk_lt_i32 s11, 0x400
	s_waitcnt lgkmcnt(0)
	v_mfma_f32_32x32x16_bf16 v[0:15], v[202:205], v[70:73], v[0:15]
	ds_read_b128 v[202:205], v174 offset:34880
	s_waitcnt lgkmcnt(0)
	v_mfma_f32_32x32x16_bf16 v[0:15], v[202:205], v[66:69], v[0:15]
	ds_read_b128 v[202:205], v174 offset:34912
	s_waitcnt lgkmcnt(0)
	v_mfma_f32_32x32x16_bf16 v[0:15], v[202:205], v[62:65], v[0:15]
	ds_read_b128 v[202:205], v174 offset:34944
	s_waitcnt lgkmcnt(0)
	v_mfma_f32_32x32x16_bf16 v[0:15], v[202:205], v[58:61], v[0:15]
	ds_read_b128 v[202:205], v174 offset:34976
	s_waitcnt lgkmcnt(0)
	v_mfma_f32_32x32x16_bf16 v[0:15], v[202:205], v[54:57], v[0:15]
	ds_read_b128 v[202:205], v174 offset:35008
	s_waitcnt lgkmcnt(0)
	v_mfma_f32_32x32x16_bf16 v[0:15], v[202:205], v[50:53], v[0:15]
	ds_read_b128 v[202:205], v174 offset:35040
	s_waitcnt lgkmcnt(0)
	v_mfma_f32_32x32x16_bf16 v[0:15], v[202:205], v[46:49], v[0:15]
	s_nop 11
	v_mul_f32_e32 v0, v0, v201
	v_mul_f32_e32 v201, v200, v105
	v_exp_f32_e32 v201, v201
	s_nop 0
	v_mul_f32_e32 v1, v1, v201
	v_mul_f32_e32 v201, v200, v106
	v_exp_f32_e32 v201, v201
	v_cvt_pk_bf16_f32 v0, v0, v1
	s_nop 0
	v_mul_f32_e32 v2, v2, v201
	v_mul_f32_e32 v201, v200, v107
	v_exp_f32_e32 v201, v201
	s_nop 0
	v_mul_f32_e32 v3, v3, v201
	v_cvt_pk_bf16_f32 v1, v2, v3
	ds_write_b64 v177, v[0:1]
	v_mul_f32_e32 v0, v200, v108
	v_mul_f32_e32 v1, v200, v109
	v_exp_f32_e32 v0, v0
	v_exp_f32_e32 v1, v1
	v_mul_f32_e32 v2, v200, v110
	v_mul_f32_e32 v3, v200, v111
	v_exp_f32_e32 v2, v2
	v_exp_f32_e32 v3, v3
	v_mul_f32_e32 v0, v4, v0
	v_mul_f32_e32 v1, v5, v1
	v_mul_f32_e32 v2, v6, v2
	v_mul_f32_e32 v3, v7, v3
	v_cvt_pk_bf16_f32 v0, v0, v1
	v_cvt_pk_bf16_f32 v1, v2, v3
	ds_write_b64 v190, v[0:1]
	v_mul_f32_e32 v0, v200, v112
	v_mul_f32_e32 v1, v200, v113
	v_exp_f32_e32 v0, v0
	v_exp_f32_e32 v1, v1
	v_mul_f32_e32 v2, v200, v114
	v_mul_f32_e32 v3, v200, v115
	v_exp_f32_e32 v2, v2
	v_exp_f32_e32 v3, v3
	v_mul_f32_e32 v0, v8, v0
	v_mul_f32_e32 v1, v9, v1
	v_mul_f32_e32 v2, v10, v2
	v_mul_f32_e32 v3, v11, v3
	v_cvt_pk_bf16_f32 v0, v0, v1
	v_cvt_pk_bf16_f32 v1, v2, v3
	ds_write_b64 v191, v[0:1]
	v_mul_f32_e32 v0, v200, v116
	v_mul_f32_e32 v1, v200, v117
	v_exp_f32_e32 v0, v0
	v_exp_f32_e32 v1, v1
	v_mul_f32_e32 v2, v200, v118
	v_mul_f32_e32 v3, v200, v119
	v_exp_f32_e32 v2, v2
	v_exp_f32_e32 v3, v3
	v_mul_f32_e32 v0, v12, v0
	v_mul_f32_e32 v1, v13, v1
	v_mul_f32_e32 v2, v14, v2
	v_mul_f32_e32 v3, v15, v3
	v_cvt_pk_bf16_f32 v0, v0, v1
	v_cvt_pk_bf16_f32 v1, v2, v3
	ds_write_b64 v192, v[0:1]
	ds_read_b128 v[0:3], v174 offset:43520
	ds_read_b128 v[202:205], v174 offset:43552
	s_waitcnt lgkmcnt(1)
	v_mfma_f32_32x32x16_bf16 v[0:15], v[0:3], v[74:77], 0
	v_mul_f32_e32 v201, v200, v120
	v_exp_f32_e32 v201, v201
	s_waitcnt lgkmcnt(0)
	v_mfma_f32_32x32x16_bf16 v[0:15], v[202:205], v[70:73], v[0:15]
	ds_read_b128 v[202:205], v174 offset:43584
	s_waitcnt lgkmcnt(0)
	v_mfma_f32_32x32x16_bf16 v[0:15], v[202:205], v[66:69], v[0:15]
	ds_read_b128 v[202:205], v174 offset:43616
	s_waitcnt lgkmcnt(0)
	v_mfma_f32_32x32x16_bf16 v[0:15], v[202:205], v[62:65], v[0:15]
	ds_read_b128 v[202:205], v174 offset:43648
	s_waitcnt lgkmcnt(0)
	v_mfma_f32_32x32x16_bf16 v[0:15], v[202:205], v[58:61], v[0:15]
	ds_read_b128 v[202:205], v174 offset:43680
	s_waitcnt lgkmcnt(0)
	v_mfma_f32_32x32x16_bf16 v[0:15], v[202:205], v[54:57], v[0:15]
	ds_read_b128 v[202:205], v174 offset:43712
	s_waitcnt lgkmcnt(0)
	v_mfma_f32_32x32x16_bf16 v[0:15], v[202:205], v[50:53], v[0:15]
	ds_read_b128 v[202:205], v174 offset:43744
	s_waitcnt lgkmcnt(0)
	v_mfma_f32_32x32x16_bf16 v[0:15], v[202:205], v[46:49], v[0:15]
	s_nop 11
	v_mul_f32_e32 v0, v201, v0
	v_mul_f32_e32 v201, v200, v121
	v_exp_f32_e32 v201, v201
	s_nop 0
	v_mul_f32_e32 v1, v201, v1
	v_mul_f32_e32 v201, v200, v122
	v_exp_f32_e32 v201, v201
	v_cvt_pk_bf16_f32 v0, v0, v1
	s_nop 0
	v_mul_f32_e32 v2, v201, v2
	v_mul_f32_e32 v201, v200, v123
	v_exp_f32_e32 v201, v201
	s_nop 0
	v_mul_f32_e32 v3, v201, v3
	v_cvt_pk_bf16_f32 v1, v2, v3
	ds_write_b64 v193, v[0:1]
	v_mul_f32_e32 v0, v200, v124
	v_mul_f32_e32 v1, v200, v125
	v_exp_f32_e32 v0, v0
	v_exp_f32_e32 v1, v1
	v_mul_f32_e32 v2, v200, v126
	v_mul_f32_e32 v3, v200, v127
	v_exp_f32_e32 v2, v2
	v_exp_f32_e32 v3, v3
	v_mul_f32_e32 v0, v0, v4
	v_mul_f32_e32 v1, v1, v5
	v_mul_f32_e32 v2, v2, v6
	v_mul_f32_e32 v3, v3, v7
	v_cvt_pk_bf16_f32 v0, v0, v1
	v_cvt_pk_bf16_f32 v1, v2, v3
	ds_write_b64 v194, v[0:1]
	v_mul_f32_e32 v0, v200, v128
	v_mul_f32_e32 v1, v200, v129
	v_exp_f32_e32 v0, v0
	v_exp_f32_e32 v1, v1
	v_mul_f32_e32 v2, v200, v130
	v_mul_f32_e32 v3, v200, v131
	v_exp_f32_e32 v2, v2
	v_exp_f32_e32 v3, v3
	v_mul_f32_e32 v0, v0, v8
	v_mul_f32_e32 v1, v1, v9
	v_mul_f32_e32 v2, v2, v10
	v_mul_f32_e32 v3, v3, v11
	v_cvt_pk_bf16_f32 v0, v0, v1
	v_cvt_pk_bf16_f32 v1, v2, v3
	ds_write_b64 v195, v[0:1]
	v_mul_f32_e32 v0, v200, v132
	v_mul_f32_e32 v1, v200, v133
	v_exp_f32_e32 v0, v0
	v_exp_f32_e32 v1, v1
	v_mul_f32_e32 v2, v200, v134
	v_mul_f32_e32 v3, v200, v135
	v_exp_f32_e32 v2, v2
	v_exp_f32_e32 v3, v3
	v_mul_f32_e32 v0, v0, v12
	v_mul_f32_e32 v1, v1, v13
	v_mul_f32_e32 v2, v2, v14
	v_mul_f32_e32 v3, v3, v15
	v_cvt_pk_bf16_f32 v0, v0, v1
	v_cvt_pk_bf16_f32 v1, v2, v3
	ds_write_b64 v196, v[0:1]
	s_waitcnt lgkmcnt(0)
	s_barrier
	s_waitcnt vmcnt(7)
	ds_write_b128 v185, v[16:19] offset:34816
	s_waitcnt vmcnt(5)
	ds_write_b128 v197, v[20:23] offset:34816
	s_waitcnt vmcnt(3)
	ds_write_b128 v198, v[24:27] offset:34816
	s_waitcnt vmcnt(1)
	ds_write_b128 v199, v[28:31] offset:34816
	s_waitcnt lgkmcnt(0)
	s_barrier
	ds_read_b128 v[0:3], v174 offset:34816
	ds_read_b128 v[16:19], v174 offset:34848
	s_waitcnt lgkmcnt(1)
	v_mfma_f32_32x32x16_bf16 v[0:15], v[74:77], v[0:3], 0
	ds_read_b128 v[202:205], v174 offset:43552
	v_mul_f32_e32 v201, v200, v136
	v_cmp_gt_f32_e32 vcc, s20, v201
	s_nop 1
	v_cndmask_b32_e32 v201, 0, v228, vcc
	v_fmac_f32_e32 v201, v200, v136
	s_waitcnt lgkmcnt(1)
	v_mfma_f32_32x32x16_bf16 v[0:15], v[70:73], v[16:19], v[0:15]
	ds_read_b128 v[16:19], v174 offset:34880
	v_exp_f32_e32 v201, v201
	s_waitcnt lgkmcnt(0)
	v_mfma_f32_32x32x16_bf16 v[0:15], v[66:69], v[16:19], v[0:15]
	ds_read_b128 v[16:19], v174 offset:34912
	s_waitcnt lgkmcnt(0)
	v_mfma_f32_32x32x16_bf16 v[0:15], v[62:65], v[16:19], v[0:15]
	ds_read_b128 v[16:19], v174 offset:34944
	s_waitcnt lgkmcnt(0)
	v_mfma_f32_32x32x16_bf16 v[0:15], v[58:61], v[16:19], v[0:15]
	ds_read_b128 v[16:19], v174 offset:34976
	s_waitcnt lgkmcnt(0)
	v_mfma_f32_32x32x16_bf16 v[0:15], v[54:57], v[16:19], v[0:15]
	ds_read_b128 v[16:19], v174 offset:35008
	s_waitcnt lgkmcnt(0)
	v_mfma_f32_32x32x16_bf16 v[0:15], v[50:53], v[16:19], v[0:15]
	ds_read_b128 v[16:19], v174 offset:35040
	s_waitcnt lgkmcnt(0)
	v_mfma_f32_32x32x16_bf16 v[0:15], v[46:49], v[16:19], v[0:15]
	ds_read_b128 v[16:19], v174 offset:43520
	s_waitcnt lgkmcnt(0)
	v_mfma_f32_32x32x16_bf16 v[16:31], v[74:77], v[16:19], 0
	v_mfma_f32_32x32x16_bf16 v[16:31], v[70:73], v[202:205], v[16:31]
	ds_read_b128 v[202:205], v174 offset:43584
	s_waitcnt lgkmcnt(0)
	v_mfma_f32_32x32x16_bf16 v[16:31], v[66:69], v[202:205], v[16:31]
	ds_read_b128 v[202:205], v174 offset:43616
	s_waitcnt lgkmcnt(0)
	v_mfma_f32_32x32x16_bf16 v[16:31], v[62:65], v[202:205], v[16:31]
	ds_read_b128 v[202:205], v174 offset:43648
	s_waitcnt lgkmcnt(0)
	v_mfma_f32_32x32x16_bf16 v[16:31], v[58:61], v[202:205], v[16:31]
	ds_read_b128 v[202:205], v174 offset:43680
	s_waitcnt lgkmcnt(0)
	v_mfma_f32_32x32x16_bf16 v[16:31], v[54:57], v[202:205], v[16:31]
	ds_read_b128 v[202:205], v174 offset:43712
	s_waitcnt lgkmcnt(0)
	v_mfma_f32_32x32x16_bf16 v[16:31], v[50:53], v[202:205], v[16:31]
	ds_read_b128 v[202:205], v174 offset:43744
	s_waitcnt lgkmcnt(0)
	s_barrier
	ds_write_b128 v185, v[34:37] offset:34816
	ds_write_b128 v197, v[38:41] offset:34816
	ds_write_b128 v198, v[42:45] offset:34816
	s_waitcnt vmcnt(0)
	ds_write_b128 v199, v[78:81] offset:34816
	s_waitcnt lgkmcnt(0)
	s_barrier
	v_lshl_add_u64 v[252:253], s[0:1], 0, v[90:91]
	v_mul_lo_u32 v250, v252, s97
	v_mov_b32_e32 v251, v33
	v_lshl_add_u64 v[250:251], v[250:251], 0, v[98:99]
	v_lshl_add_u64 v[250:251], v[250:251], 0, s[88:89]
	v_lshl_add_u64 v[250:251], v[250:251], 0, v[32:33]
	v_mov_b32_e32 v253, v33
	v_mov_b32_e32 v252, 0x2000
	v_lshl_add_u64 v[242:243], v[250:251], 0, v[252:253]
	global_load_dwordx4 v[242:245], v[242:243], off offset:2048
	v_mov_b32_e32 v252, 0xd000
	v_lshl_add_u64 v[246:247], v[250:251], 0, v[252:253]
	global_load_dwordx4 v[246:249], v[246:247], off offset:2048
	v_mov_b32_e32 v252, 0x18000
	v_lshl_add_u64 v[78:79], v[250:251], 0, v[252:253]
	global_load_dwordx4 v[78:81], v[78:79], off offset:2048
	v_mov_b32_e32 v252, 0x23000
	v_lshl_add_u64 v[250:251], v[250:251], 0, v[252:253]
	global_load_dwordx4 v[250:253], v[250:251], off offset:2048
	v_mfma_f32_32x32x16_bf16 v[16:31], v[46:49], v[202:205], v[16:31]
	v_cndmask_b32_e32 v202, 0, v223, vcc
	v_ldexp_f32 v202, v201, v202
	v_mul_f32_e32 v201, v200, v137
	v_cmp_gt_f32_e32 vcc, s20, v201
	ds_read_b128 v[34:37], v174 offset:34816
	ds_read_b128 v[38:41], v174 offset:34848
	v_cndmask_b32_e32 v201, 0, v228, vcc
	v_fmac_f32_e32 v201, v200, v137
	v_exp_f32_e32 v201, v201
	v_cndmask_b32_e32 v203, 0, v223, vcc
	v_ldexp_f32 v203, v201, v203
	v_mul_f32_e32 v201, v200, v138
	v_cmp_gt_f32_e32 vcc, s20, v201
	v_pk_mul_f32 v[0:1], v[202:203], v[0:1]
	v_pk_mul_f32 v[16:17], v[202:203], v[16:17]
	v_cndmask_b32_e32 v201, 0, v228, vcc
	v_fmac_f32_e32 v201, v200, v138
	v_exp_f32_e32 v201, v201
	v_cndmask_b32_e32 v204, 0, v223, vcc
	v_ldexp_f32 v204, v201, v204
	v_mul_f32_e32 v201, v200, v139
	v_cmp_gt_f32_e32 vcc, s20, v201
	s_nop 1
	v_cndmask_b32_e32 v201, 0, v228, vcc
	v_fmac_f32_e32 v201, v200, v139
	v_exp_f32_e32 v201, v201
	v_cndmask_b32_e32 v205, 0, v223, vcc
	v_ldexp_f32 v205, v201, v205
	v_mul_f32_e32 v201, v200, v140
	v_cmp_gt_f32_e32 vcc, s20, v201
	v_pk_mul_f32 v[2:3], v[204:205], v[2:3]
	v_pk_mul_f32 v[18:19], v[204:205], v[18:19]
	v_cndmask_b32_e32 v201, 0, v228, vcc
	v_fmac_f32_e32 v201, v200, v140
	v_exp_f32_e32 v201, v201
	v_cndmask_b32_e32 v206, 0, v223, vcc
	v_ldexp_f32 v206, v201, v206
	v_mul_f32_e32 v201, v200, v141
	v_cmp_gt_f32_e32 vcc, s20, v201
	s_nop 1
	v_cndmask_b32_e32 v201, 0, v228, vcc
	v_fmac_f32_e32 v201, v200, v141
	v_exp_f32_e32 v201, v201
	v_cndmask_b32_e32 v207, 0, v223, vcc
	v_ldexp_f32 v207, v201, v207
	v_mul_f32_e32 v201, v200, v142
	v_cmp_gt_f32_e32 vcc, s20, v201
	v_pk_mul_f32 v[4:5], v[206:207], v[4:5]
	v_pk_mul_f32 v[20:21], v[206:207], v[20:21]
	v_cndmask_b32_e32 v201, 0, v228, vcc
	v_fmac_f32_e32 v201, v200, v142
	v_exp_f32_e32 v201, v201
	v_cndmask_b32_e32 v208, 0, v223, vcc
	v_ldexp_f32 v208, v201, v208
	v_mul_f32_e32 v201, v200, v143
	v_cmp_gt_f32_e32 vcc, s20, v201
	s_nop 1
	v_cndmask_b32_e32 v201, 0, v228, vcc
	v_fmac_f32_e32 v201, v200, v143
	v_exp_f32_e32 v201, v201
	v_cndmask_b32_e32 v209, 0, v223, vcc
	v_ldexp_f32 v209, v201, v209
	v_mul_f32_e32 v201, v200, v144
	v_cmp_gt_f32_e32 vcc, s20, v201
	v_pk_mul_f32 v[6:7], v[208:209], v[6:7]
	v_pk_mul_f32 v[22:23], v[208:209], v[22:23]
	v_cndmask_b32_e32 v201, 0, v228, vcc
	v_fmac_f32_e32 v201, v200, v144
	v_exp_f32_e32 v201, v201
	v_cndmask_b32_e32 v234, 0, v223, vcc
	v_ldexp_f32 v234, v201, v234
	v_mul_f32_e32 v201, v200, v145
	v_cmp_gt_f32_e32 vcc, s20, v201
	s_nop 1
	v_cndmask_b32_e32 v201, 0, v228, vcc
	v_fmac_f32_e32 v201, v200, v145
	v_exp_f32_e32 v201, v201
	v_cndmask_b32_e32 v235, 0, v223, vcc
	v_ldexp_f32 v235, v201, v235
	v_mul_f32_e32 v201, v200, v146
	v_cmp_gt_f32_e32 vcc, s20, v201
	v_pk_mul_f32 v[8:9], v[234:235], v[8:9]
	v_pk_mul_f32 v[24:25], v[234:235], v[24:25]
	v_cndmask_b32_e32 v201, 0, v228, vcc
	v_fmac_f32_e32 v201, v200, v146
	v_exp_f32_e32 v201, v201
	v_cndmask_b32_e32 v236, 0, v223, vcc
	v_ldexp_f32 v236, v201, v236
	v_mul_f32_e32 v201, v200, v147
	v_cmp_gt_f32_e32 vcc, s20, v201
	s_nop 1
	v_cndmask_b32_e32 v201, 0, v228, vcc
	v_fmac_f32_e32 v201, v200, v147
	v_exp_f32_e32 v201, v201
	v_cndmask_b32_e32 v237, 0, v223, vcc
	v_ldexp_f32 v237, v201, v237
	v_mul_f32_e32 v201, v200, v148
	v_cmp_gt_f32_e32 vcc, s20, v201
	v_pk_mul_f32 v[10:11], v[236:237], v[10:11]
	v_pk_mul_f32 v[26:27], v[236:237], v[26:27]
	v_cndmask_b32_e32 v201, 0, v228, vcc
	v_fmac_f32_e32 v201, v200, v148
	v_exp_f32_e32 v201, v201
	v_cndmask_b32_e32 v238, 0, v223, vcc
	v_ldexp_f32 v238, v201, v238
	v_mul_f32_e32 v201, v200, v149
	v_cmp_gt_f32_e32 vcc, s20, v201
	s_nop 1
	v_cndmask_b32_e32 v201, 0, v228, vcc
	v_fmac_f32_e32 v201, v200, v149
	v_exp_f32_e32 v201, v201
	v_cndmask_b32_e32 v239, 0, v223, vcc
	v_ldexp_f32 v239, v201, v239
	v_mul_f32_e32 v201, v200, v150
	v_cmp_gt_f32_e32 vcc, s20, v201
	v_pk_mul_f32 v[12:13], v[238:239], v[12:13]
	v_pk_mul_f32 v[28:29], v[238:239], v[28:29]
	v_cndmask_b32_e32 v201, 0, v228, vcc
	v_fmac_f32_e32 v201, v200, v150
	v_exp_f32_e32 v201, v201
	v_cndmask_b32_e32 v240, 0, v223, vcc
	v_ldexp_f32 v240, v201, v240
	v_mul_f32_e32 v201, v200, v151
	v_cmp_gt_f32_e32 vcc, s20, v201
	s_nop 1
	v_cndmask_b32_e32 v201, 0, v228, vcc
	v_fmac_f32_e32 v201, v200, v151
	v_exp_f32_e32 v201, v201
	v_cndmask_b32_e32 v241, 0, v223, vcc
	v_ldexp_f32 v241, v201, v241
	v_pk_mul_f32 v[14:15], v[240:241], v[14:15]
	v_pk_mul_f32 v[30:31], v[240:241], v[30:31]
	s_waitcnt lgkmcnt(1)
	v_mfma_f32_32x32x16_bf16 v[0:15], v[74:77], v[34:37], v[0:15]
	ds_read_b128 v[34:37], v174 offset:34880
	s_waitcnt lgkmcnt(1)
	v_mfma_f32_32x32x16_bf16 v[0:15], v[70:73], v[38:41], v[0:15]
	s_waitcnt lgkmcnt(0)
	v_mfma_f32_32x32x16_bf16 v[0:15], v[66:69], v[34:37], v[0:15]
	ds_read_b128 v[34:37], v174 offset:34912
	s_waitcnt lgkmcnt(0)
	v_mfma_f32_32x32x16_bf16 v[0:15], v[62:65], v[34:37], v[0:15]
	ds_read_b128 v[34:37], v174 offset:34944
	s_waitcnt lgkmcnt(0)
	v_mfma_f32_32x32x16_bf16 v[0:15], v[58:61], v[34:37], v[0:15]
	ds_read_b128 v[34:37], v174 offset:34976
	s_waitcnt lgkmcnt(0)
	v_mfma_f32_32x32x16_bf16 v[0:15], v[54:57], v[34:37], v[0:15]
	ds_read_b128 v[34:37], v174 offset:35008
	s_waitcnt lgkmcnt(0)
	v_mfma_f32_32x32x16_bf16 v[0:15], v[50:53], v[34:37], v[0:15]
	ds_read_b128 v[34:37], v174 offset:35040
	s_waitcnt lgkmcnt(0)
	v_mfma_f32_32x32x16_bf16 v[0:15], v[46:49], v[34:37], v[0:15]
	ds_read_b128 v[34:37], v174 offset:43520
	s_waitcnt lgkmcnt(0)
	v_mfma_f32_32x32x16_bf16 v[16:31], v[74:77], v[34:37], v[16:31]
	ds_read_b128 v[34:37], v174 offset:43552
	s_waitcnt lgkmcnt(0)
	v_mfma_f32_32x32x16_bf16 v[16:31], v[70:73], v[34:37], v[16:31]
	ds_read_b128 v[34:37], v174 offset:43584
	s_waitcnt lgkmcnt(0)
	v_mfma_f32_32x32x16_bf16 v[16:31], v[66:69], v[34:37], v[16:31]
	ds_read_b128 v[34:37], v174 offset:43616
	s_waitcnt lgkmcnt(0)
	v_mfma_f32_32x32x16_bf16 v[16:31], v[62:65], v[34:37], v[16:31]
	ds_read_b128 v[34:37], v174 offset:43648
	s_waitcnt lgkmcnt(0)
	v_mfma_f32_32x32x16_bf16 v[16:31], v[58:61], v[34:37], v[16:31]
	ds_read_b128 v[34:37], v174 offset:43680
	s_waitcnt lgkmcnt(0)
	v_mfma_f32_32x32x16_bf16 v[16:31], v[54:57], v[34:37], v[16:31]
	ds_read_b128 v[34:37], v174 offset:43712
	v_add_u32_e32 v54, s92, v169
	s_waitcnt lgkmcnt(0)
	v_mfma_f32_32x32x16_bf16 v[16:31], v[50:53], v[34:37], v[16:31]
	ds_read_b128 v[34:37], v174 offset:43744
	s_waitcnt lgkmcnt(0)
	v_mfma_f32_32x32x16_bf16 v[16:31], v[46:49], v[34:37], v[16:31]
	v_mul_f32_e32 v34, v200, v152
	v_cmp_gt_f32_e32 vcc, s20, v34
	s_nop 1
	v_cndmask_b32_e32 v34, 0, v228, vcc
	v_fmac_f32_e32 v34, v200, v152
	v_exp_f32_e32 v34, v34
	v_cndmask_b32_e32 v35, 0, v223, vcc
	v_ldexp_f32 v34, v34, v35
	v_mul_f32_e32 v35, v200, v153
	v_cmp_gt_f32_e32 vcc, s20, v35
	s_nop 1
	v_cndmask_b32_e32 v35, 0, v228, vcc
	v_fmac_f32_e32 v35, v200, v153
	v_exp_f32_e32 v35, v35
	v_cndmask_b32_e32 v36, 0, v223, vcc
	v_ldexp_f32 v35, v35, v36
	v_mul_f32_e32 v36, v200, v154
	v_cmp_gt_f32_e32 vcc, s20, v36
	v_pk_mul_f32 v[0:1], v[34:35], v[0:1]
	v_pk_mul_f32 v[16:17], v[34:35], v[16:17]
	v_cndmask_b32_e32 v36, 0, v228, vcc
	v_fmac_f32_e32 v36, v200, v154
	v_exp_f32_e32 v36, v36
	v_cndmask_b32_e32 v37, 0, v223, vcc
	v_ldexp_f32 v36, v36, v37
	v_mul_f32_e32 v37, v200, v155
	v_cmp_gt_f32_e32 vcc, s20, v37
	s_nop 1
	v_cndmask_b32_e32 v37, 0, v228, vcc
	v_fmac_f32_e32 v37, v200, v155
	v_exp_f32_e32 v37, v37
	v_cndmask_b32_e32 v38, 0, v223, vcc
	v_ldexp_f32 v37, v37, v38
	v_mul_f32_e32 v38, v200, v156
	v_cmp_gt_f32_e32 vcc, s20, v38
	v_pk_mul_f32 v[2:3], v[36:37], v[2:3]
	v_pk_mul_f32 v[18:19], v[36:37], v[18:19]
	v_cndmask_b32_e32 v38, 0, v228, vcc
	v_fmac_f32_e32 v38, v200, v156
	v_exp_f32_e32 v38, v38
	v_cndmask_b32_e32 v39, 0, v223, vcc
	v_ldexp_f32 v38, v38, v39
	v_mul_f32_e32 v39, v200, v157
	v_cmp_gt_f32_e32 vcc, s20, v39
	s_nop 1
	v_cndmask_b32_e32 v39, 0, v228, vcc
	v_fmac_f32_e32 v39, v200, v157
	v_exp_f32_e32 v39, v39
	v_cndmask_b32_e32 v40, 0, v223, vcc
	v_ldexp_f32 v39, v39, v40
	v_mul_f32_e32 v40, v200, v158
	v_cmp_gt_f32_e32 vcc, s20, v40
	v_pk_mul_f32 v[4:5], v[38:39], v[4:5]
	v_pk_mul_f32 v[20:21], v[38:39], v[20:21]
	v_cndmask_b32_e32 v40, 0, v228, vcc
	v_fmac_f32_e32 v40, v200, v158
	v_exp_f32_e32 v40, v40
	v_cndmask_b32_e32 v41, 0, v223, vcc
	v_ldexp_f32 v40, v40, v41
	v_mul_f32_e32 v41, v200, v159
	v_cmp_gt_f32_e32 vcc, s20, v41
	s_nop 1
	v_cndmask_b32_e32 v41, 0, v228, vcc
	v_fmac_f32_e32 v41, v200, v159
	v_exp_f32_e32 v41, v41
	v_cndmask_b32_e32 v42, 0, v223, vcc
	v_ldexp_f32 v41, v41, v42
	v_mul_f32_e32 v42, v200, v160
	v_cmp_gt_f32_e32 vcc, s20, v42
	v_pk_mul_f32 v[6:7], v[40:41], v[6:7]
	v_pk_mul_f32 v[22:23], v[40:41], v[22:23]
	v_cndmask_b32_e32 v42, 0, v228, vcc
	v_fmac_f32_e32 v42, v200, v160
	v_exp_f32_e32 v42, v42
	v_cndmask_b32_e32 v43, 0, v223, vcc
	v_ldexp_f32 v42, v42, v43
	v_mul_f32_e32 v43, v200, v161
	v_cmp_gt_f32_e32 vcc, s20, v43
	s_nop 1
	v_cndmask_b32_e32 v43, 0, v228, vcc
	v_fmac_f32_e32 v43, v200, v161
	v_exp_f32_e32 v43, v43
	v_cndmask_b32_e32 v44, 0, v223, vcc
	v_ldexp_f32 v43, v43, v44
	v_mul_f32_e32 v44, v200, v162
	v_cmp_gt_f32_e32 vcc, s20, v44
	v_pk_mul_f32 v[8:9], v[42:43], v[8:9]
	v_pk_mul_f32 v[24:25], v[42:43], v[24:25]
	v_cndmask_b32_e32 v44, 0, v228, vcc
	v_fmac_f32_e32 v44, v200, v162
	v_exp_f32_e32 v44, v44
	v_cndmask_b32_e32 v45, 0, v223, vcc
	v_ldexp_f32 v44, v44, v45
	v_mul_f32_e32 v45, v200, v163
	v_cmp_gt_f32_e32 vcc, s20, v45
	s_nop 1
	v_cndmask_b32_e32 v45, 0, v228, vcc
	v_fmac_f32_e32 v45, v200, v163
	v_exp_f32_e32 v45, v45
	v_cndmask_b32_e32 v46, 0, v223, vcc
	v_ldexp_f32 v45, v45, v46
	v_mul_f32_e32 v46, v200, v164
	v_cmp_gt_f32_e32 vcc, s20, v46
	v_pk_mul_f32 v[10:11], v[44:45], v[10:11]
	v_pk_mul_f32 v[26:27], v[44:45], v[26:27]
	v_cndmask_b32_e32 v46, 0, v228, vcc
	v_fmac_f32_e32 v46, v200, v164
	v_exp_f32_e32 v46, v46
	v_cndmask_b32_e32 v47, 0, v223, vcc
	v_ldexp_f32 v46, v46, v47
	v_mul_f32_e32 v47, v200, v165
	v_cmp_gt_f32_e32 vcc, s20, v47
	s_nop 1
	v_cndmask_b32_e32 v47, 0, v228, vcc
	v_fmac_f32_e32 v47, v200, v165
	v_exp_f32_e32 v47, v47
	v_cndmask_b32_e32 v48, 0, v223, vcc
	v_ldexp_f32 v47, v47, v48
	v_mul_f32_e32 v48, v200, v166
	v_cmp_gt_f32_e32 vcc, s20, v48
	v_pk_mul_f32 v[12:13], v[46:47], v[12:13]
	v_pk_mul_f32 v[28:29], v[46:47], v[28:29]
	v_cndmask_b32_e32 v48, 0, v228, vcc
	v_fmac_f32_e32 v48, v200, v166
	v_exp_f32_e32 v48, v48
	v_cndmask_b32_e32 v49, 0, v223, vcc
	v_ldexp_f32 v48, v48, v49
	v_mul_f32_e32 v49, v200, v167
	v_cmp_gt_f32_e32 vcc, s20, v49
	s_nop 1
	v_cndmask_b32_e32 v49, 0, v228, vcc
	v_fmac_f32_e32 v49, v200, v167
	v_exp_f32_e32 v49, v49
	v_cndmask_b32_e32 v50, 0, v223, vcc
	v_ldexp_f32 v49, v49, v50
	v_pk_mul_f32 v[14:15], v[48:49], v[14:15]
	v_pk_mul_f32 v[30:31], v[48:49], v[30:31]
	ds_read_b64_tr_b16 v[46:47], v168 offset:0
	ds_read_b64_tr_b16 v[48:49], v168 offset:1088
	ds_read_b64_tr_b16 v[42:43], v168 offset:64
	ds_read_b64_tr_b16 v[44:45], v168 offset:1152
	ds_read_b64_tr_b16 v[38:39], v168 offset:4352
	ds_read_b64_tr_b16 v[40:41], v168 offset:5440
	ds_read_b64_tr_b16 v[34:35], v168 offset:4416
	ds_read_b64_tr_b16 v[36:37], v168 offset:5504
	s_waitcnt lgkmcnt(0)
	ds_read_b128 v[50:53], v54
	s_waitcnt lgkmcnt(0)
	v_mfma_f32_32x32x16_bf16 v[0:15], v[50:53], v[46:49], v[0:15]
	v_mfma_f32_32x32x16_bf16 v[16:31], v[50:53], v[42:45], v[16:31]
	v_add_u32_e32 v42, 0, v169
	v_add_u32_e32 v55, 0x11020, v42
	ds_read_b128 v[42:45], v55
	s_waitcnt lgkmcnt(0)
	v_mfma_f32_32x32x16_bf16 v[0:15], v[42:45], v[38:41], v[0:15]
	v_mfma_f32_32x32x16_bf16 v[16:31], v[42:45], v[34:37], v[16:31]
	ds_read_b64_tr_b16 v[46:47], v170 offset:0
	ds_read_b64_tr_b16 v[48:49], v170 offset:1088
	ds_read_b64_tr_b16 v[42:43], v170 offset:64
	ds_read_b64_tr_b16 v[44:45], v170 offset:1152
	ds_read_b64_tr_b16 v[38:39], v170 offset:4352
	ds_read_b64_tr_b16 v[40:41], v170 offset:5440
	ds_read_b64_tr_b16 v[34:35], v170 offset:4416
	ds_read_b64_tr_b16 v[36:37], v170 offset:5504
	s_waitcnt lgkmcnt(0)
	ds_read_b128 v[50:53], v54 offset:64
	s_waitcnt lgkmcnt(0)
	v_mfma_f32_32x32x16_bf16 v[16:31], v[50:53], v[42:45], v[16:31]
	ds_read_b128 v[42:45], v55 offset:64
	v_mfma_f32_32x32x16_bf16 v[0:15], v[50:53], v[46:49], v[0:15]
	s_waitcnt lgkmcnt(0)
	v_mfma_f32_32x32x16_bf16 v[0:15], v[42:45], v[38:41], v[0:15]
	v_mfma_f32_32x32x16_bf16 v[16:31], v[42:45], v[34:37], v[16:31]
	ds_read_b64_tr_b16 v[46:47], v171 offset:0
	ds_read_b64_tr_b16 v[48:49], v171 offset:1088
	ds_read_b64_tr_b16 v[42:43], v171 offset:64
	ds_read_b64_tr_b16 v[44:45], v171 offset:1152
	ds_read_b64_tr_b16 v[38:39], v171 offset:4352
	ds_read_b64_tr_b16 v[40:41], v171 offset:5440
	ds_read_b64_tr_b16 v[34:35], v171 offset:4416
	ds_read_b64_tr_b16 v[36:37], v171 offset:5504
	s_waitcnt lgkmcnt(0)
	ds_read_b128 v[50:53], v54 offset:128
	s_waitcnt lgkmcnt(0)
	v_mfma_f32_32x32x16_bf16 v[16:31], v[50:53], v[42:45], v[16:31]
	ds_read_b128 v[42:45], v55 offset:128
	v_mfma_f32_32x32x16_bf16 v[0:15], v[50:53], v[46:49], v[0:15]
	s_waitcnt lgkmcnt(0)
	v_mfma_f32_32x32x16_bf16 v[0:15], v[42:45], v[38:41], v[0:15]
	v_mfma_f32_32x32x16_bf16 v[16:31], v[42:45], v[34:37], v[16:31]
	ds_read_b64_tr_b16 v[46:47], v172 offset:0
	ds_read_b64_tr_b16 v[48:49], v172 offset:1088
	ds_read_b64_tr_b16 v[42:43], v172 offset:64
	ds_read_b64_tr_b16 v[44:45], v172 offset:1152
	ds_read_b64_tr_b16 v[38:39], v172 offset:4352
	ds_read_b64_tr_b16 v[40:41], v172 offset:5440
	ds_read_b64_tr_b16 v[34:35], v172 offset:4416
	ds_read_b64_tr_b16 v[36:37], v172 offset:5504
	s_waitcnt lgkmcnt(0)
	ds_read_b128 v[50:53], v54 offset:192
	s_waitcnt lgkmcnt(0)
	v_mfma_f32_32x32x16_bf16 v[16:31], v[50:53], v[42:45], v[16:31]
	ds_read_b128 v[42:45], v55 offset:192
	s_waitcnt lgkmcnt(0)
	s_barrier
	v_mfma_f32_32x32x16_bf16 v[0:15], v[50:53], v[46:49], v[0:15]
	v_mfma_f32_32x32x16_bf16 v[0:15], v[42:45], v[38:41], v[0:15]
	v_mfma_f32_32x32x16_bf16 v[16:31], v[42:45], v[34:37], v[16:31]
	s_nop 11
	ds_write2_b32 v175, v0, v16 offset1:32
	ds_write2_b32 v175, v1, v17 offset0:132 offset1:164
	v_add_u32_e32 v0, 0x400, v175
	ds_write2_b32 v0, v2, v18 offset0:8 offset1:40
	ds_write2_b32 v0, v3, v19 offset0:140 offset1:172
	v_add_u32_e32 v0, 0x1000, v175
	ds_write2_b32 v0, v4, v20 offset0:32 offset1:64
	ds_write2_b32 v0, v5, v21 offset0:164 offset1:196
	v_add_u32_e32 v0, 0x1400, v175
	ds_write2_b32 v0, v6, v22 offset0:40 offset1:72
	ds_write2_b32 v0, v7, v23 offset0:172 offset1:204
	v_add_u32_e32 v0, 0x2000, v175
	ds_write2_b32 v0, v8, v24 offset0:64 offset1:96
	ds_write2_b32 v0, v9, v25 offset0:196 offset1:228
	v_add_u32_e32 v0, 0x2400, v175
	ds_write2_b32 v0, v10, v26 offset0:72 offset1:104
	ds_write2_b32 v0, v11, v27 offset0:204 offset1:236
	v_add_u32_e32 v0, 0x3000, v175
	ds_write2_b32 v0, v12, v28 offset0:96 offset1:128
	v_add_u32_e32 v0, 0x3200, v175
	ds_write2_b32 v0, v13, v29 offset0:100 offset1:132
	v_add_u32_e32 v0, 0x3400, v175
	ds_write2_b32 v0, v14, v30 offset0:104 offset1:136
	v_add_u32_e32 v0, 0x3600, v175
	ds_write2_b32 v0, v15, v31 offset0:108 offset1:140
	v_lshl_add_u64 v[0:1], v[88:89], 0, s[8:9]
	v_lshl_add_u64 v[24:25], s[0:1], 0, v[90:91]
	global_load_dwordx4 v[12:15], v[0:1], off offset:16
	global_load_dwordx4 v[16:19], v[0:1], off
	s_waitcnt lgkmcnt(0)
	s_barrier
	ds_read_b128 v[46:49], v176
	ds_read_b128 v[50:53], v176 offset:16
	ds_read_b128 v[54:57], v176 offset:2112
	ds_read_b128 v[58:61], v176 offset:2128
	ds_read_b128 v[62:65], v176 offset:4224
	ds_read_b128 v[66:69], v176 offset:4240
	ds_read_b128 v[70:73], v176 offset:6336
	ds_read_b128 v[74:77], v176 offset:6352
	s_waitcnt lgkmcnt(6)
	v_add_f32_e32 v34, 0, v46
	v_add_f32_e32 v34, v47, v34
	v_add_f32_e32 v34, v48, v34
	v_add_f32_e32 v34, v49, v34
	v_add_f32_e32 v34, v50, v34
	v_add_f32_e32 v34, v51, v34
	v_add_f32_e32 v34, v52, v34
	v_add_f32_e32 v34, v53, v34
	s_waitcnt lgkmcnt(4)
	v_add_f32_e32 v35, 0, v54
	v_add_f32_e32 v35, v55, v35
	v_add_f32_e32 v35, v56, v35
	v_add_f32_e32 v35, v57, v35
	v_add_f32_e32 v35, v58, v35
	v_add_f32_e32 v35, v59, v35
	v_add_f32_e32 v35, v60, v35
	v_add_f32_e32 v35, v61, v35
	s_waitcnt lgkmcnt(2)
	v_add_f32_e32 v36, 0, v62
	v_add_f32_e32 v36, v63, v36
	v_add_f32_e32 v36, v64, v36
	v_add_f32_e32 v36, v65, v36
	v_add_f32_e32 v36, v66, v36
	v_add_f32_e32 v36, v67, v36
	v_add_f32_e32 v36, v68, v36
	v_add_f32_e32 v36, v69, v36
	s_waitcnt lgkmcnt(0)
	v_add_f32_e32 v37, 0, v70
	v_add_f32_e32 v37, v71, v37
	v_add_f32_e32 v37, v72, v37
	v_add_f32_e32 v37, v73, v37
	v_add_f32_e32 v37, v74, v37
	v_add_f32_e32 v37, v75, v37
	v_add_f32_e32 v37, v76, v37
	v_add_f32_e32 v37, v77, v37
	ds_bpermute_b32 v38, v233, v34
	ds_bpermute_b32 v39, v233, v35
	ds_bpermute_b32 v40, v233, v36
	ds_bpermute_b32 v30, v233, v37
	s_waitcnt lgkmcnt(3)
	v_add_f32_e32 v34, v34, v38
	s_waitcnt lgkmcnt(2)
	v_add_f32_e32 v35, v35, v39
	s_waitcnt lgkmcnt(1)
	v_add_f32_e32 v36, v36, v40
	s_waitcnt lgkmcnt(0)
	v_add_f32_e32 v37, v37, v30
	ds_bpermute_b32 v38, v232, v34
	ds_bpermute_b32 v39, v232, v35
	ds_bpermute_b32 v40, v232, v36
	ds_bpermute_b32 v30, v232, v37
	s_waitcnt lgkmcnt(3)
	v_add_f32_e32 v34, v34, v38
	s_waitcnt lgkmcnt(2)
	v_add_f32_e32 v35, v35, v39
	s_waitcnt lgkmcnt(1)
	v_add_f32_e32 v36, v36, v40
	s_waitcnt lgkmcnt(0)
	v_add_f32_e32 v37, v37, v30
	ds_bpermute_b32 v38, v231, v34
	ds_bpermute_b32 v39, v231, v35
	ds_bpermute_b32 v40, v231, v36
	ds_bpermute_b32 v30, v231, v37
	s_waitcnt lgkmcnt(3)
	v_add_f32_e32 v34, v34, v38
	s_waitcnt lgkmcnt(2)
	v_add_f32_e32 v35, v35, v39
	s_waitcnt lgkmcnt(1)
	v_add_f32_e32 v36, v36, v40
	s_waitcnt lgkmcnt(0)
	v_add_f32_e32 v37, v37, v30
	ds_bpermute_b32 v38, v230, v34
	ds_bpermute_b32 v39, v230, v35
	ds_bpermute_b32 v40, v230, v36
	ds_bpermute_b32 v30, v230, v37
	s_waitcnt lgkmcnt(3)
	v_add_f32_e32 v34, v34, v38
	s_waitcnt lgkmcnt(2)
	v_add_f32_e32 v35, v35, v39
	s_waitcnt lgkmcnt(1)
	v_add_f32_e32 v36, v36, v40
	s_waitcnt lgkmcnt(0)
	v_add_f32_e32 v37, v37, v30
	v_mul_f32_e32 v38, 0x3c000000, v34
	v_mul_f32_e32 v39, 0x3c000000, v35
	v_mul_f32_e32 v40, 0x3c000000, v36
	v_mul_f32_e32 v30, 0x3c000000, v37
	v_sub_f32_e32 v46, v46, v38
	v_sub_f32_e32 v47, v47, v38
	v_sub_f32_e32 v48, v48, v38
	v_sub_f32_e32 v49, v49, v38
	v_sub_f32_e32 v50, v50, v38
	v_sub_f32_e32 v51, v51, v38
	v_sub_f32_e32 v52, v52, v38
	v_sub_f32_e32 v53, v53, v38
	v_sub_f32_e32 v54, v54, v39
	v_sub_f32_e32 v55, v55, v39
	v_sub_f32_e32 v56, v56, v39
	v_sub_f32_e32 v57, v57, v39
	v_sub_f32_e32 v58, v58, v39
	v_sub_f32_e32 v59, v59, v39
	v_sub_f32_e32 v60, v60, v39
	v_sub_f32_e32 v61, v61, v39
	v_sub_f32_e32 v62, v62, v40
	v_sub_f32_e32 v63, v63, v40
	v_sub_f32_e32 v64, v64, v40
	v_sub_f32_e32 v65, v65, v40
	v_sub_f32_e32 v66, v66, v40
	v_sub_f32_e32 v67, v67, v40
	v_sub_f32_e32 v68, v68, v40
	v_sub_f32_e32 v69, v69, v40
	v_sub_f32_e32 v70, v70, v30
	v_sub_f32_e32 v71, v71, v30
	v_sub_f32_e32 v72, v72, v30
	v_sub_f32_e32 v73, v73, v30
	v_sub_f32_e32 v74, v74, v30
	v_sub_f32_e32 v75, v75, v30
	v_sub_f32_e32 v76, v76, v30
	v_sub_f32_e32 v77, v77, v30
	v_mul_f32_e32 v34, v47, v47
	v_fmac_f32_e32 v34, v46, v46
	v_mul_f32_e32 v35, v55, v55
	v_fmac_f32_e32 v35, v54, v54
	v_mul_f32_e32 v36, v63, v63
	v_fmac_f32_e32 v36, v62, v62
	v_mul_f32_e32 v37, v71, v71
	v_fmac_f32_e32 v37, v70, v70
	v_mul_f32_e32 v38, v48, v48
	v_mul_f32_e32 v39, v56, v56
	v_mul_f32_e32 v40, v64, v64
	v_mul_f32_e32 v30, v72, v72
	v_add_f32_e32 v34, v38, v34
	v_add_f32_e32 v35, v39, v35
	v_add_f32_e32 v36, v40, v36
	v_add_f32_e32 v37, v30, v37
	v_mul_f32_e32 v38, v49, v49
	v_mul_f32_e32 v39, v57, v57
	v_mul_f32_e32 v40, v65, v65
	v_mul_f32_e32 v30, v73, v73
	v_add_f32_e32 v34, v38, v34
	v_add_f32_e32 v35, v39, v35
	v_add_f32_e32 v36, v40, v36
	v_add_f32_e32 v37, v30, v37
	v_mul_f32_e32 v38, v50, v50
	v_mul_f32_e32 v39, v58, v58
	v_mul_f32_e32 v40, v66, v66
	v_mul_f32_e32 v30, v74, v74
	v_add_f32_e32 v34, v38, v34
	v_add_f32_e32 v35, v39, v35
	v_add_f32_e32 v36, v40, v36
	v_add_f32_e32 v37, v30, v37
	v_mul_f32_e32 v38, v51, v51
	v_mul_f32_e32 v39, v59, v59
	v_mul_f32_e32 v40, v67, v67
	v_mul_f32_e32 v30, v75, v75
	v_add_f32_e32 v34, v38, v34
	v_add_f32_e32 v35, v39, v35
	v_add_f32_e32 v36, v40, v36
	v_add_f32_e32 v37, v30, v37
	v_mul_f32_e32 v38, v52, v52
	v_mul_f32_e32 v39, v60, v60
	v_mul_f32_e32 v40, v68, v68
	v_mul_f32_e32 v30, v76, v76
	v_add_f32_e32 v34, v38, v34
	v_add_f32_e32 v35, v39, v35
	v_add_f32_e32 v36, v40, v36
	v_add_f32_e32 v37, v30, v37
	v_mul_f32_e32 v38, v53, v53
	v_mul_f32_e32 v39, v61, v61
	v_mul_f32_e32 v40, v69, v69
	v_mul_f32_e32 v30, v77, v77
	v_add_f32_e32 v34, v38, v34
	v_add_f32_e32 v35, v39, v35
	v_add_f32_e32 v36, v40, v36
	v_add_f32_e32 v37, v30, v37
	ds_bpermute_b32 v38, v233, v34
	ds_bpermute_b32 v39, v233, v35
	ds_bpermute_b32 v40, v233, v36
	ds_bpermute_b32 v30, v233, v37
	s_waitcnt lgkmcnt(3)
	v_add_f32_e32 v34, v34, v38
	s_waitcnt lgkmcnt(2)
	v_add_f32_e32 v35, v35, v39
	s_waitcnt lgkmcnt(1)
	v_add_f32_e32 v36, v36, v40
	s_waitcnt lgkmcnt(0)
	v_add_f32_e32 v37, v37, v30
	ds_bpermute_b32 v38, v232, v34
	ds_bpermute_b32 v39, v232, v35
	ds_bpermute_b32 v40, v232, v36
	ds_bpermute_b32 v30, v232, v37
	s_waitcnt lgkmcnt(3)
	v_add_f32_e32 v34, v34, v38
	s_waitcnt lgkmcnt(2)
	v_add_f32_e32 v35, v35, v39
	s_waitcnt lgkmcnt(1)
	v_add_f32_e32 v36, v36, v40
	s_waitcnt lgkmcnt(0)
	v_add_f32_e32 v37, v37, v30
	ds_bpermute_b32 v38, v231, v34
	ds_bpermute_b32 v39, v231, v35
	ds_bpermute_b32 v40, v231, v36
	ds_bpermute_b32 v30, v231, v37
	s_waitcnt lgkmcnt(3)
	v_add_f32_e32 v34, v34, v38
	s_waitcnt lgkmcnt(2)
	v_add_f32_e32 v35, v35, v39
	s_waitcnt lgkmcnt(1)
	v_add_f32_e32 v36, v36, v40
	s_waitcnt lgkmcnt(0)
	v_add_f32_e32 v37, v37, v30
	ds_bpermute_b32 v38, v230, v34
	ds_bpermute_b32 v39, v230, v35
	ds_bpermute_b32 v40, v230, v36
	ds_bpermute_b32 v30, v230, v37
	s_waitcnt lgkmcnt(3)
	v_add_f32_e32 v34, v34, v38
	s_waitcnt lgkmcnt(2)
	v_add_f32_e32 v35, v35, v39
	s_waitcnt lgkmcnt(1)
	v_add_f32_e32 v36, v36, v40
	s_waitcnt lgkmcnt(0)
	v_add_f32_e32 v37, v37, v30
	v_fmamk_f32 v34, v34, 0x3c000000, v218
	v_cmp_gt_f32_e32 vcc, s18, v34
	v_mul_f32_e32 v38, 0x4b800000, v34
	s_nop 0
	v_cndmask_b32_e32 v34, v34, v38, vcc
	v_rsq_f32_e32 v34, v34
	s_nop 0
	v_mul_f32_e32 v38, 0x45800000, v34
	v_cndmask_b32_e32 v34, v34, v38, vcc
	v_fmamk_f32 v35, v35, 0x3c000000, v218
	v_cmp_gt_f32_e32 vcc, s18, v35
	v_mul_f32_e32 v39, 0x4b800000, v35
	s_nop 0
	v_cndmask_b32_e32 v35, v35, v39, vcc
	v_rsq_f32_e32 v35, v35
	s_nop 0
	v_mul_f32_e32 v39, 0x45800000, v35
	v_cndmask_b32_e32 v35, v35, v39, vcc
	v_fmamk_f32 v36, v36, 0x3c000000, v218
	v_cmp_gt_f32_e32 vcc, s18, v36
	v_mul_f32_e32 v40, 0x4b800000, v36
	s_nop 0
	v_cndmask_b32_e32 v36, v36, v40, vcc
	v_rsq_f32_e32 v36, v36
	s_nop 0
	v_mul_f32_e32 v40, 0x45800000, v36
	v_cndmask_b32_e32 v36, v36, v40, vcc
	v_fmamk_f32 v37, v37, 0x3c000000, v218
	v_cmp_gt_f32_e32 vcc, s18, v37
	v_mul_f32_e32 v30, 0x4b800000, v37
	s_nop 0
	v_cndmask_b32_e32 v37, v37, v30, vcc
	v_rsq_f32_e32 v37, v37
	s_nop 0
	v_mul_f32_e32 v30, 0x45800000, v37
	v_cndmask_b32_e32 v37, v37, v30, vcc
	s_waitcnt vmcnt(0)
	v_mul_f32_e32 v46, v46, v34
	v_mul_f32_e32 v46, v16, v46
	v_mul_f32_e32 v47, v47, v34
	v_mul_f32_e32 v47, v17, v47
	v_mul_f32_e32 v48, v48, v34
	v_mul_f32_e32 v48, v18, v48
	v_mul_f32_e32 v49, v49, v34
	v_mul_f32_e32 v49, v19, v49
	v_mul_f32_e32 v50, v50, v34
	v_mul_f32_e32 v50, v12, v50
	v_mul_f32_e32 v51, v51, v34
	v_mul_f32_e32 v51, v13, v51
	v_mul_f32_e32 v52, v52, v34
	v_mul_f32_e32 v52, v14, v52
	v_mul_f32_e32 v53, v53, v34
	v_mul_f32_e32 v53, v15, v53
	v_lshlrev_b32_e32 v26, 16, v242
	v_and_b32_e32 v27, 0xffff0000, v242
	v_mul_f32_e32 v26, v46, v26
	v_mul_f32_e32 v27, v47, v27
	v_cvt_pk_bf16_f32 v0, v26, v27
	v_lshlrev_b32_e32 v26, 16, v243
	v_and_b32_e32 v27, 0xffff0000, v243
	v_mul_f32_e32 v26, v48, v26
	v_mul_f32_e32 v27, v49, v27
	v_cvt_pk_bf16_f32 v1, v26, v27
	v_lshlrev_b32_e32 v26, 16, v244
	v_and_b32_e32 v27, 0xffff0000, v244
	v_mul_f32_e32 v26, v50, v26
	v_mul_f32_e32 v27, v51, v27
	v_cvt_pk_bf16_f32 v2, v26, v27
	v_lshlrev_b32_e32 v26, 16, v245
	v_and_b32_e32 v27, 0xffff0000, v245
	v_mul_f32_e32 v26, v52, v26
	v_mul_f32_e32 v27, v53, v27
	v_cvt_pk_bf16_f32 v3, v26, v27
	v_mul_f32_e32 v54, v54, v35
	v_mul_f32_e32 v54, v16, v54
	v_mul_f32_e32 v55, v55, v35
	v_mul_f32_e32 v55, v17, v55
	v_mul_f32_e32 v56, v56, v35
	v_mul_f32_e32 v56, v18, v56
	v_mul_f32_e32 v57, v57, v35
	v_mul_f32_e32 v57, v19, v57
	v_mul_f32_e32 v58, v58, v35
	v_mul_f32_e32 v58, v12, v58
	v_mul_f32_e32 v59, v59, v35
	v_mul_f32_e32 v59, v13, v59
	v_mul_f32_e32 v60, v60, v35
	v_mul_f32_e32 v60, v14, v60
	v_mul_f32_e32 v61, v61, v35
	v_mul_f32_e32 v61, v15, v61
	v_lshlrev_b32_e32 v26, 16, v246
	v_and_b32_e32 v27, 0xffff0000, v246
	v_mul_f32_e32 v26, v54, v26
	v_mul_f32_e32 v27, v55, v27
	v_cvt_pk_bf16_f32 v4, v26, v27
	v_lshlrev_b32_e32 v26, 16, v247
	v_and_b32_e32 v27, 0xffff0000, v247
	v_mul_f32_e32 v26, v56, v26
	v_mul_f32_e32 v27, v57, v27
	v_cvt_pk_bf16_f32 v5, v26, v27
	v_lshlrev_b32_e32 v26, 16, v248
	v_and_b32_e32 v27, 0xffff0000, v248
	v_mul_f32_e32 v26, v58, v26
	v_mul_f32_e32 v27, v59, v27
	v_cvt_pk_bf16_f32 v6, v26, v27
	v_lshlrev_b32_e32 v26, 16, v249
	v_and_b32_e32 v27, 0xffff0000, v249
	v_mul_f32_e32 v26, v60, v26
	v_mul_f32_e32 v27, v61, v27
	v_cvt_pk_bf16_f32 v7, v26, v27
	v_mul_f32_e32 v62, v62, v36
	v_mul_f32_e32 v62, v16, v62
	v_mul_f32_e32 v63, v63, v36
	v_mul_f32_e32 v63, v17, v63
	v_mul_f32_e32 v64, v64, v36
	v_mul_f32_e32 v64, v18, v64
	v_mul_f32_e32 v65, v65, v36
	v_mul_f32_e32 v65, v19, v65
	v_mul_f32_e32 v66, v66, v36
	v_mul_f32_e32 v66, v12, v66
	v_mul_f32_e32 v67, v67, v36
	v_mul_f32_e32 v67, v13, v67
	v_mul_f32_e32 v68, v68, v36
	v_mul_f32_e32 v68, v14, v68
	v_mul_f32_e32 v69, v69, v36
	v_mul_f32_e32 v69, v15, v69
	v_lshlrev_b32_e32 v26, 16, v78
	v_and_b32_e32 v27, 0xffff0000, v78
	v_mul_f32_e32 v26, v62, v26
	v_mul_f32_e32 v27, v63, v27
	v_cvt_pk_bf16_f32 v8, v26, v27
	v_lshlrev_b32_e32 v26, 16, v79
	v_and_b32_e32 v27, 0xffff0000, v79
	v_mul_f32_e32 v26, v64, v26
	v_mul_f32_e32 v27, v65, v27
	v_cvt_pk_bf16_f32 v9, v26, v27
	v_lshlrev_b32_e32 v26, 16, v80
	v_and_b32_e32 v27, 0xffff0000, v80
	v_mul_f32_e32 v26, v66, v26
	v_mul_f32_e32 v27, v67, v27
	v_cvt_pk_bf16_f32 v10, v26, v27
	v_lshlrev_b32_e32 v26, 16, v81
	v_and_b32_e32 v27, 0xffff0000, v81
	v_mul_f32_e32 v26, v68, v26
	v_mul_f32_e32 v27, v69, v27
	v_cvt_pk_bf16_f32 v11, v26, v27
	v_mul_f32_e32 v70, v70, v37
	v_mul_f32_e32 v70, v16, v70
	v_mul_f32_e32 v71, v71, v37
	v_mul_f32_e32 v71, v17, v71
	v_mul_f32_e32 v72, v72, v37
	v_mul_f32_e32 v72, v18, v72
	v_mul_f32_e32 v73, v73, v37
	v_mul_f32_e32 v73, v19, v73
	v_mul_f32_e32 v74, v74, v37
	v_mul_f32_e32 v74, v12, v74
	v_mul_f32_e32 v75, v75, v37
	v_mul_f32_e32 v75, v13, v75
	v_mul_f32_e32 v76, v76, v37
	v_mul_f32_e32 v76, v14, v76
	v_mul_f32_e32 v77, v77, v37
	v_mul_f32_e32 v77, v15, v77
	v_lshlrev_b32_e32 v26, 16, v250
	v_and_b32_e32 v27, 0xffff0000, v250
	v_mul_f32_e32 v26, v70, v26
	v_mul_f32_e32 v27, v71, v27
	v_cvt_pk_bf16_f32 v20, v26, v27
	v_lshlrev_b32_e32 v26, 16, v251
	v_and_b32_e32 v27, 0xffff0000, v251
	v_mul_f32_e32 v26, v72, v26
	v_mul_f32_e32 v27, v73, v27
	v_cvt_pk_bf16_f32 v21, v26, v27
	v_lshlrev_b32_e32 v26, 16, v252
	v_and_b32_e32 v27, 0xffff0000, v252
	v_mul_f32_e32 v26, v74, v26
	v_mul_f32_e32 v27, v75, v27
	v_cvt_pk_bf16_f32 v22, v26, v27
	v_lshlrev_b32_e32 v26, 16, v253
	v_and_b32_e32 v27, 0xffff0000, v253
	v_mul_f32_e32 v26, v76, v26
	v_mul_f32_e32 v27, v77, v27
	v_cvt_pk_bf16_f32 v23, v26, v27
	v_lshlrev_b64 v[26:27], 12, v[24:25]
	v_mov_b32_e32 v28, v26
	v_mov_b32_e32 v29, v27
	v_lshl_add_u64 v[28:29], s[4:5], 0, v[28:29]
	v_lshl_add_u64 v[28:29], v[28:29], 0, s[88:89]
	v_lshl_add_u64 v[28:29], v[28:29], 0, v[32:33]
	v_add_co_u32_e32 v28, vcc, s24, v28
	s_nop 1
	v_addc_co_u32_e32 v29, vcc, 0, v29, vcc
	global_store_dwordx4 v[28:29], v[0:3], off offset:3072
	v_or_b32_e32 v28, 0x4000, v26
	v_mov_b32_e32 v29, v27
	v_lshl_add_u64 v[28:29], s[4:5], 0, v[28:29]
	v_lshl_add_u64 v[28:29], v[28:29], 0, s[88:89]
	v_lshl_add_u64 v[28:29], v[28:29], 0, v[32:33]
	v_add_co_u32_e32 v28, vcc, s24, v28
	s_nop 1
	v_addc_co_u32_e32 v29, vcc, 0, v29, vcc
	global_store_dwordx4 v[28:29], v[4:7], off offset:3072
	v_or_b32_e32 v28, 0x8000, v26
	v_mov_b32_e32 v29, v27
	v_lshl_add_u64 v[28:29], s[4:5], 0, v[28:29]
	v_lshl_add_u64 v[28:29], v[28:29], 0, s[88:89]
	v_lshl_add_u64 v[28:29], v[28:29], 0, v[32:33]
	v_add_co_u32_e32 v28, vcc, s24, v28
	s_nop 1
	v_addc_co_u32_e32 v29, vcc, 0, v29, vcc
	global_store_dwordx4 v[28:29], v[8:11], off offset:3072
	v_or_b32_e32 v28, 0xc000, v26
	v_mov_b32_e32 v29, v27
	v_lshl_add_u64 v[28:29], s[4:5], 0, v[28:29]
	v_lshl_add_u64 v[28:29], v[28:29], 0, s[88:89]
	v_lshl_add_u64 v[28:29], v[28:29], 0, v[32:33]
	v_add_co_u32_e32 v28, vcc, s24, v28
	s_nop 1
	v_addc_co_u32_e32 v29, vcc, 0, v29, vcc
	global_store_dwordx4 v[28:29], v[20:23], off offset:3072
	s_cbranch_scc1 .LBB0_802
